# L1 invalidates removed at the three grid barriers and the prep-ready point where no buffer read afterwards was loaded by this CU before (one invalidate per layer transition kept)
# speedup vs baseline: 1.0329x; 1.0231x over previous
.LBB0_240:
	s_or_b64 exec, exec, s[8:9]
	s_waitcnt vmcnt(0) lgkmcnt(0)
	s_nop 0
	s_waitcnt vmcnt(0)

.LBB0_258:
	s_or_b64 exec, exec, s[2:3]
	s_mov_b64 s[2:3], exec
	v_mbcnt_lo_u32_b32 v0, s2, 0
	v_mbcnt_hi_u32_b32 v0, s3, v0
	s_mov_b32 s11, 0
	v_cmp_eq_u32_e32 vcc, 0, v0
	s_waitcnt vmcnt(0)
	s_nop 0
	s_and_saveexec_b64 s[8:9], vcc
	s_cbranch_execz .LBB0_260
	s_add_i32 s10, s24, 0x900
	s_lshl_b64 s[10:11], s[10:11], 2
	v_readlane_b32 s12, v252, 0
	v_readlane_b32 s13, v252, 1
	s_add_u32 s10, s12, s10
	s_addc_u32 s11, s13, s11
	s_bcnt1_i32_b64 s2, s[2:3]
	v_mov_b32_e32 v0, 0
	v_mov_b32_e32 v1, s2
	global_atomic_add v0, v1, s[10:11]

.LBB0_366:
	s_or_b64 exec, exec, s[2:3]
	s_mov_b64 s[2:3], exec
	v_mbcnt_lo_u32_b32 v0, s2, 0
	v_mbcnt_hi_u32_b32 v0, s3, v0
	v_cmp_eq_u32_e32 vcc, 0, v0
	s_waitcnt vmcnt(0)
	s_nop 0
	s_and_saveexec_b64 s[8:9], vcc
	s_cbranch_execz .LBB0_368
	s_mov_b64 s[12:13], 0x3e38aa3b
	s_add_i32 s10, s22, 0x900
	s_mov_b32 s11, s13
	s_lshl_b64 s[10:11], s[10:11], 2
	v_readlane_b32 s12, v252, 0
	v_readlane_b32 s13, v252, 1
	s_add_u32 s10, s12, s10
	s_addc_u32 s11, s13, s11
	s_bcnt1_i32_b64 s2, s[2:3]
	v_mov_b32_e32 v0, s2
	global_atomic_add v193, v0, s[10:11]

.LBB0_423:
	s_or_b64 exec, exec, s[0:1]
	s_nop 0
	s_waitcnt vmcnt(0)
	v_readlane_b32 s10, v254, 51
